# epilogue waits moved to first consumer: P3 hook, P3/P4/P6 epilogues replace their single vmcnt(0) after the operand loads by counted waits at each load's first use
# speedup vs baseline: 1.0105x; 1.0028x over previous
.Lhook3_go:
	s_mov_b64 s[4:5], s[84:85]
	s_and_b32 s5, s5, 0xffff
	buffer_load_dwordx4 v[176:179], v174, s[4:7], s51 offen
	buffer_load_dwordx4 v[180:183], v174, s[4:7], s52 offen
	buffer_load_dwordx4 v[184:187], v174, s[4:7], 0 offen
	buffer_load_dwordx4 v[188:191], v174, s[4:7], s46 offen
	buffer_load_dwordx4 v[192:195], v174, s[4:7], s50 offen
	buffer_load_dwordx4 v[218:221], v174, s[4:7], s49 offen
	buffer_load_dwordx4 v[222:225], v174, s[4:7], s53 offen
	buffer_load_dwordx4 v[166:169], v174, s[4:7], s54 offen
	buffer_load_dwordx4 v[162:165], v174, s[4:7], s55 offen
	buffer_load_dwordx4 v[158:161], v174, s[4:7], s56 offen
	buffer_load_dwordx4 v[154:157], v174, s[4:7], s57 offen
	buffer_load_dwordx4 v[150:153], v174, s[4:7], s58 offen
	buffer_load_dwordx4 v[146:149], v174, s[4:7], s59 offen
	buffer_load_dwordx4 v[142:145], v174, s[4:7], s60 offen
	buffer_load_dwordx4 v[138:141], v174, s[4:7], s61 offen
	buffer_load_dwordx4 v[134:137], v174, s[4:7], s62 offen
	s_waitcnt vmcnt(13)
	v_lshlrev_b32_e32 v4, 16, v184
	v_and_b32_e32 v5, 0xffff0000, v184
	v_pk_mul_f32 v[130:131], v[130:131], v[4:5]
	v_lshlrev_b32_e32 v4, 16, v186
	v_and_b32_e32 v5, 0xffff0000, v186
	v_pk_mul_f32 v[126:127], v[126:127], v[4:5]
	v_lshlrev_b32_e32 v4, 16, v176
	v_and_b32_e32 v5, 0xffff0000, v176
	v_pk_mul_f32 v[122:123], v[122:123], v[4:5]
	v_lshlrev_b32_e32 v4, 16, v178
	v_and_b32_e32 v5, 0xffff0000, v178
	v_pk_mul_f32 v[118:119], v[118:119], v[4:5]
	s_waitcnt vmcnt(11)
	v_lshlrev_b32_e32 v4, 16, v192
	v_and_b32_e32 v5, 0xffff0000, v192
	v_pk_mul_f32 v[114:115], v[114:115], v[4:5]
	v_lshlrev_b32_e32 v4, 16, v194
	v_and_b32_e32 v5, 0xffff0000, v194
	v_pk_mul_f32 v[110:111], v[110:111], v[4:5]
	v_lshlrev_b32_e32 v4, 16, v180
	v_and_b32_e32 v5, 0xffff0000, v180
	v_pk_mul_f32 v[106:107], v[106:107], v[4:5]
	v_lshlrev_b32_e32 v4, 16, v182
	v_and_b32_e32 v5, 0xffff0000, v182
	v_pk_mul_f32 v[102:103], v[102:103], v[4:5]
	v_lshlrev_b32_e32 v4, 16, v188
	v_and_b32_e32 v5, 0xffff0000, v188
	v_pk_mul_f32 v[98:99], v[98:99], v[4:5]
	v_lshlrev_b32_e32 v4, 16, v190
	v_and_b32_e32 v5, 0xffff0000, v190
	v_pk_mul_f32 v[94:95], v[94:95], v[4:5]
	s_waitcnt vmcnt(9)
	v_lshlrev_b32_e32 v4, 16, v222
	v_and_b32_e32 v5, 0xffff0000, v222
	v_pk_mul_f32 v[90:91], v[90:91], v[4:5]
	v_lshlrev_b32_e32 v4, 16, v224
	v_and_b32_e32 v5, 0xffff0000, v224
	v_pk_mul_f32 v[86:87], v[86:87], v[4:5]
	v_lshlrev_b32_e32 v4, 16, v218
	v_and_b32_e32 v5, 0xffff0000, v218
	v_pk_mul_f32 v[82:83], v[82:83], v[4:5]
	v_lshlrev_b32_e32 v4, 16, v220
	v_and_b32_e32 v5, 0xffff0000, v220
	v_pk_mul_f32 v[78:79], v[78:79], v[4:5]
	s_waitcnt vmcnt(8)
	v_lshlrev_b32_e32 v4, 16, v166
	v_and_b32_e32 v5, 0xffff0000, v166
	v_pk_mul_f32 v[74:75], v[74:75], v[4:5]
	v_lshlrev_b32_e32 v4, 16, v168
	v_and_b32_e32 v5, 0xffff0000, v168
	v_pk_mul_f32 v[70:71], v[70:71], v[4:5]
	s_waitcnt vmcnt(7)
	v_lshlrev_b32_e32 v4, 16, v162
	v_and_b32_e32 v5, 0xffff0000, v162
	v_pk_mul_f32 v[66:67], v[66:67], v[4:5]
	v_lshlrev_b32_e32 v4, 16, v164
	v_and_b32_e32 v5, 0xffff0000, v164
	v_pk_mul_f32 v[62:63], v[62:63], v[4:5]
	s_waitcnt vmcnt(6)
	v_lshlrev_b32_e32 v4, 16, v158
	v_and_b32_e32 v5, 0xffff0000, v158
	v_pk_mul_f32 v[58:59], v[58:59], v[4:5]
	v_lshlrev_b32_e32 v4, 16, v160
	v_and_b32_e32 v5, 0xffff0000, v160
	v_lshlrev_b32_e32 v176, 16, v177
	v_and_b32_e32 v177, 0xffff0000, v177
	v_pk_mul_f32 v[54:55], v[54:55], v[4:5]
	s_waitcnt vmcnt(5)
	v_lshlrev_b32_e32 v4, 16, v154
	v_and_b32_e32 v5, 0xffff0000, v154
	v_pk_mul_f32 v[124:125], v[124:125], v[176:177]
	v_lshlrev_b32_e32 v176, 16, v179
	v_and_b32_e32 v177, 0xffff0000, v179
	v_pk_mul_f32 v[50:51], v[50:51], v[4:5]
	v_lshlrev_b32_e32 v4, 16, v156
	v_and_b32_e32 v5, 0xffff0000, v156
	v_pk_mul_f32 v[120:121], v[120:121], v[176:177]
	v_lshlrev_b32_e32 v176, 16, v193
	v_and_b32_e32 v177, 0xffff0000, v193
	v_pk_mul_f32 v[46:47], v[46:47], v[4:5]
	s_waitcnt vmcnt(4)
	v_lshlrev_b32_e32 v4, 16, v150
	v_and_b32_e32 v5, 0xffff0000, v150
	v_pk_mul_f32 v[116:117], v[116:117], v[176:177]
	v_lshlrev_b32_e32 v176, 16, v195
	v_and_b32_e32 v177, 0xffff0000, v195
	v_pk_mul_f32 v[42:43], v[42:43], v[4:5]
	v_lshlrev_b32_e32 v4, 16, v152
	v_and_b32_e32 v5, 0xffff0000, v152
	v_pk_mul_f32 v[112:113], v[112:113], v[176:177]
	v_lshlrev_b32_e32 v176, 16, v181
	v_and_b32_e32 v177, 0xffff0000, v181
	v_pk_mul_f32 v[38:39], v[38:39], v[4:5]
	s_waitcnt vmcnt(3)
	v_lshlrev_b32_e32 v4, 16, v146
	v_and_b32_e32 v5, 0xffff0000, v146
	v_pk_mul_f32 v[108:109], v[108:109], v[176:177]
	v_lshlrev_b32_e32 v176, 16, v183
	v_and_b32_e32 v177, 0xffff0000, v183
	v_pk_mul_f32 v[34:35], v[34:35], v[4:5]
	v_lshlrev_b32_e32 v4, 16, v148
	v_and_b32_e32 v5, 0xffff0000, v148
	v_pk_mul_f32 v[104:105], v[104:105], v[176:177]
	v_lshlrev_b32_e32 v176, 16, v189
	v_and_b32_e32 v177, 0xffff0000, v189
	v_pk_mul_f32 v[30:31], v[30:31], v[4:5]
	s_waitcnt vmcnt(2)
	v_lshlrev_b32_e32 v4, 16, v142
	v_and_b32_e32 v5, 0xffff0000, v142
	v_pk_mul_f32 v[100:101], v[100:101], v[176:177]
	v_lshlrev_b32_e32 v176, 16, v191
	v_and_b32_e32 v177, 0xffff0000, v191
	v_pk_mul_f32 v[26:27], v[26:27], v[4:5]
	v_lshlrev_b32_e32 v4, 16, v144
	v_and_b32_e32 v5, 0xffff0000, v144
	v_pk_mul_f32 v[96:97], v[96:97], v[176:177]
	v_lshlrev_b32_e32 v176, 16, v223
	v_and_b32_e32 v177, 0xffff0000, v223
	v_pk_mul_f32 v[22:23], v[22:23], v[4:5]
	s_waitcnt vmcnt(1)
	v_lshlrev_b32_e32 v4, 16, v138
	v_and_b32_e32 v5, 0xffff0000, v138
	v_pk_mul_f32 v[92:93], v[92:93], v[176:177]
	v_lshlrev_b32_e32 v176, 16, v225
	v_and_b32_e32 v177, 0xffff0000, v225
	v_pk_mul_f32 v[18:19], v[18:19], v[4:5]
	v_lshlrev_b32_e32 v4, 16, v140
	v_and_b32_e32 v5, 0xffff0000, v140
	v_lshlrev_b32_e32 v184, 16, v185
	v_and_b32_e32 v185, 0xffff0000, v185
	v_pk_mul_f32 v[88:89], v[88:89], v[176:177]
	v_lshlrev_b32_e32 v176, 16, v219
	v_and_b32_e32 v177, 0xffff0000, v219
	v_lshlrev_b32_e32 v166, 16, v167
	v_and_b32_e32 v167, 0xffff0000, v167
	v_lshlrev_b32_e32 v162, 16, v163
	v_and_b32_e32 v163, 0xffff0000, v163
	v_lshlrev_b32_e32 v158, 16, v159
	v_and_b32_e32 v159, 0xffff0000, v159
	v_lshlrev_b32_e32 v154, 16, v155
	v_and_b32_e32 v155, 0xffff0000, v155
	v_lshlrev_b32_e32 v150, 16, v151
	v_and_b32_e32 v151, 0xffff0000, v151
	v_lshlrev_b32_e32 v146, 16, v147
	v_and_b32_e32 v147, 0xffff0000, v147
	v_lshlrev_b32_e32 v142, 16, v143
	v_and_b32_e32 v143, 0xffff0000, v143
	v_lshlrev_b32_e32 v138, 16, v139
	v_and_b32_e32 v139, 0xffff0000, v139
	v_pk_mul_f32 v[14:15], v[14:15], v[4:5]
	s_waitcnt vmcnt(0)
	v_lshlrev_b32_e32 v4, 16, v134
	v_and_b32_e32 v5, 0xffff0000, v134
	v_lshlrev_b32_e32 v134, 16, v135
	v_and_b32_e32 v135, 0xffff0000, v135
	v_pk_mul_f32 v[132:133], v[132:133], v[184:185]
	v_lshlrev_b32_e32 v184, 16, v187
	v_and_b32_e32 v185, 0xffff0000, v187
	v_pk_mul_f32 v[84:85], v[84:85], v[176:177]
	v_lshlrev_b32_e32 v176, 16, v221
	v_and_b32_e32 v177, 0xffff0000, v221
	v_pk_mul_f32 v[76:77], v[76:77], v[166:167]
	v_lshlrev_b32_e32 v166, 16, v169
	v_and_b32_e32 v167, 0xffff0000, v169
	v_pk_mul_f32 v[68:69], v[68:69], v[162:163]
	v_lshlrev_b32_e32 v162, 16, v165
	v_and_b32_e32 v163, 0xffff0000, v165
	v_pk_mul_f32 v[60:61], v[60:61], v[158:159]
	v_lshlrev_b32_e32 v158, 16, v161
	v_and_b32_e32 v159, 0xffff0000, v161
	v_pk_mul_f32 v[52:53], v[52:53], v[154:155]
	v_lshlrev_b32_e32 v154, 16, v157
	v_and_b32_e32 v155, 0xffff0000, v157
	v_pk_mul_f32 v[44:45], v[44:45], v[150:151]
	v_lshlrev_b32_e32 v150, 16, v153
	v_and_b32_e32 v151, 0xffff0000, v153
	v_pk_mul_f32 v[36:37], v[36:37], v[146:147]
	v_lshlrev_b32_e32 v146, 16, v149
	v_and_b32_e32 v147, 0xffff0000, v149
	v_pk_mul_f32 v[28:29], v[28:29], v[142:143]
	v_lshlrev_b32_e32 v142, 16, v145
	v_and_b32_e32 v143, 0xffff0000, v145
	v_pk_mul_f32 v[20:21], v[20:21], v[138:139]
	v_lshlrev_b32_e32 v138, 16, v141
	v_and_b32_e32 v139, 0xffff0000, v141
	v_pk_mul_f32 v[12:13], v[12:13], v[134:135]
	v_pk_mul_f32 v[10:11], v[10:11], v[4:5]
	v_lshlrev_b32_e32 v4, 16, v136
	v_and_b32_e32 v5, 0xffff0000, v136
	v_lshlrev_b32_e32 v134, 16, v137
	v_and_b32_e32 v135, 0xffff0000, v137
	v_pk_mul_f32 v[128:129], v[128:129], v[184:185]
	v_pk_mul_f32 v[80:81], v[80:81], v[176:177]
	v_pk_mul_f32 v[72:73], v[72:73], v[166:167]
	v_pk_mul_f32 v[64:65], v[64:65], v[162:163]
	v_pk_mul_f32 v[56:57], v[56:57], v[158:159]
	v_pk_mul_f32 v[48:49], v[48:49], v[154:155]
	v_pk_mul_f32 v[40:41], v[40:41], v[150:151]
	v_pk_mul_f32 v[32:33], v[32:33], v[146:147]
	v_pk_mul_f32 v[24:25], v[24:25], v[142:143]
	v_pk_mul_f32 v[16:17], v[16:17], v[138:139]
	v_pk_mul_f32 v[8:9], v[8:9], v[134:135]
	v_pk_mul_f32 v[6:7], v[6:7], v[4:5]
	s_andn2_b64 vcc, exec, s[8:9]
	s_cbranch_vccnz .LBB0_587
	s_barrier
	s_branch .LBB0_587

.LBB0_624:
	s_waitcnt vmcnt(15)
	v_lshlrev_b32_e32 v218, 16, v194
	v_and_b32_e32 v219, 0xffff0000, v194
	v_lshlrev_b32_e32 v194, 16, v195
	v_and_b32_e32 v195, 0xffff0000, v195
	v_pk_mul_f32 v[132:133], v[132:133], v[194:195]
	v_lshlrev_b32_e32 v194, 16, v196
	v_and_b32_e32 v195, 0xffff0000, v196
	v_lshlrev_b32_e32 v196, 16, v197
	v_and_b32_e32 v197, 0xffff0000, v197
	v_pk_mul_f32 v[196:197], v[128:129], v[196:197]
	v_pk_mul_f32 v[128:129], v[126:127], v[194:195]
	s_mov_b64 s[2:3], -1
	s_and_b64 vcc, exec, s[18:19]
	v_pk_mul_f32 v[130:131], v[130:131], v[218:219]
	s_nop 0
	v_cvt_pk_bf16_f32 v126, v130, v131
	v_cvt_pk_bf16_f32 v127, v132, v133
	v_cvt_pk_bf16_f32 v128, v128, v129
	v_cvt_pk_bf16_f32 v129, v196, v197
	s_cbranch_vccz .LBB0_626
	s_mov_b64 s[2:3], 0

.LBB0_628:
	s_nop 1
	s_waitcnt vmcnt(15)
	v_lshlrev_b32_e32 v126, 16, v190
	v_and_b32_e32 v127, 0xffff0000, v190
	v_lshlrev_b32_e32 v128, 16, v191
	v_and_b32_e32 v129, 0xffff0000, v191
	v_pk_mul_f32 v[124:125], v[124:125], v[128:129]
	v_pk_mul_f32 v[122:123], v[122:123], v[126:127]
	v_lshlrev_b32_e32 v126, 16, v192
	v_and_b32_e32 v127, 0xffff0000, v192
	v_lshlrev_b32_e32 v128, 16, v193
	v_and_b32_e32 v129, 0xffff0000, v193
	v_cndmask_b32_e64 v3, 0, 1, s[18:19]
	v_pk_mul_f32 v[128:129], v[120:121], v[128:129]
	v_pk_mul_f32 v[120:121], v[118:119], v[126:127]
	v_cmp_ne_u32_e64 s[2:3], 1, v3
	s_andn2_b64 vcc, exec, s[18:19]
	s_mov_b64 s[4:5], -1
	v_cvt_pk_bf16_f32 v118, v122, v123
	v_cvt_pk_bf16_f32 v119, v124, v125
	v_cvt_pk_bf16_f32 v120, v120, v121
	v_cvt_pk_bf16_f32 v121, v128, v129
	s_cbranch_vccnz .LBB0_630
	s_mov_b64 s[4:5], 0

.LBB0_632:
	s_nop 1
	s_waitcnt vmcnt(15)
	v_lshlrev_b32_e32 v118, 16, v186
	v_and_b32_e32 v119, 0xffff0000, v186
	v_lshlrev_b32_e32 v120, 16, v187
	v_and_b32_e32 v121, 0xffff0000, v187
	v_pk_mul_f32 v[116:117], v[116:117], v[120:121]
	v_pk_mul_f32 v[114:115], v[114:115], v[118:119]
	v_lshlrev_b32_e32 v118, 16, v188
	v_and_b32_e32 v119, 0xffff0000, v188
	v_lshlrev_b32_e32 v120, 16, v189
	v_and_b32_e32 v121, 0xffff0000, v189
	v_pk_mul_f32 v[120:121], v[112:113], v[120:121]
	v_pk_mul_f32 v[112:113], v[110:111], v[118:119]
	s_and_b64 vcc, exec, s[2:3]
	s_mov_b64 s[4:5], -1
	v_cvt_pk_bf16_f32 v110, v114, v115
	v_cvt_pk_bf16_f32 v111, v116, v117
	v_cvt_pk_bf16_f32 v112, v112, v113
	v_cvt_pk_bf16_f32 v113, v120, v121
	s_cbranch_vccnz .LBB0_634
	s_mov_b64 s[4:5], 0

.LBB0_636:
	s_nop 1
	s_waitcnt vmcnt(15)
	v_lshlrev_b32_e32 v110, 16, v182
	v_and_b32_e32 v111, 0xffff0000, v182
	v_lshlrev_b32_e32 v112, 16, v183
	v_and_b32_e32 v113, 0xffff0000, v183
	v_pk_mul_f32 v[108:109], v[108:109], v[112:113]
	v_pk_mul_f32 v[106:107], v[106:107], v[110:111]
	v_lshlrev_b32_e32 v110, 16, v184
	v_and_b32_e32 v111, 0xffff0000, v184
	v_lshlrev_b32_e32 v112, 16, v185
	v_and_b32_e32 v113, 0xffff0000, v185
	v_pk_mul_f32 v[112:113], v[104:105], v[112:113]
	v_pk_mul_f32 v[104:105], v[102:103], v[110:111]
	s_and_b64 vcc, exec, s[2:3]
	s_mov_b64 s[4:5], -1
	v_cvt_pk_bf16_f32 v102, v106, v107
	v_cvt_pk_bf16_f32 v103, v108, v109
	v_cvt_pk_bf16_f32 v104, v104, v105
	v_cvt_pk_bf16_f32 v105, v112, v113
	s_cbranch_vccnz .LBB0_638
	s_mov_b64 s[4:5], 0

.LBB0_640:
	s_nop 1
	s_waitcnt vmcnt(15)
	v_lshlrev_b32_e32 v102, 16, v178
	v_and_b32_e32 v103, 0xffff0000, v178
	v_lshlrev_b32_e32 v104, 16, v179
	v_and_b32_e32 v105, 0xffff0000, v179
	v_pk_mul_f32 v[100:101], v[100:101], v[104:105]
	v_pk_mul_f32 v[98:99], v[98:99], v[102:103]
	v_lshlrev_b32_e32 v102, 16, v180
	v_and_b32_e32 v103, 0xffff0000, v180
	v_lshlrev_b32_e32 v104, 16, v181
	v_and_b32_e32 v105, 0xffff0000, v181
	v_pk_mul_f32 v[104:105], v[96:97], v[104:105]
	v_pk_mul_f32 v[96:97], v[94:95], v[102:103]
	s_and_b64 vcc, exec, s[2:3]
	s_mov_b64 s[4:5], -1
	v_cvt_pk_bf16_f32 v94, v98, v99
	v_cvt_pk_bf16_f32 v95, v100, v101
	v_cvt_pk_bf16_f32 v96, v96, v97
	v_cvt_pk_bf16_f32 v97, v104, v105
	s_cbranch_vccnz .LBB0_642
	s_mov_b64 s[4:5], 0

.LBB0_644:
	s_nop 1
	s_waitcnt vmcnt(15)
	v_lshlrev_b32_e32 v94, 16, v174
	v_and_b32_e32 v95, 0xffff0000, v174
	v_lshlrev_b32_e32 v96, 16, v175
	v_and_b32_e32 v97, 0xffff0000, v175
	v_pk_mul_f32 v[92:93], v[92:93], v[96:97]
	v_pk_mul_f32 v[90:91], v[90:91], v[94:95]
	v_lshlrev_b32_e32 v94, 16, v176
	v_and_b32_e32 v95, 0xffff0000, v176
	v_lshlrev_b32_e32 v96, 16, v177
	v_and_b32_e32 v97, 0xffff0000, v177
	v_pk_mul_f32 v[96:97], v[88:89], v[96:97]
	v_pk_mul_f32 v[88:89], v[86:87], v[94:95]
	s_and_b64 vcc, exec, s[2:3]
	s_mov_b64 s[4:5], -1
	v_cvt_pk_bf16_f32 v86, v90, v91
	v_cvt_pk_bf16_f32 v87, v92, v93
	v_cvt_pk_bf16_f32 v88, v88, v89
	v_cvt_pk_bf16_f32 v89, v96, v97
	s_cbranch_vccnz .LBB0_646
	s_mov_b64 s[4:5], 0

.LBB0_648:
	s_nop 1
	s_waitcnt vmcnt(15)
	v_lshlrev_b32_e32 v86, 16, v170
	v_and_b32_e32 v87, 0xffff0000, v170
	v_lshlrev_b32_e32 v88, 16, v171
	v_and_b32_e32 v89, 0xffff0000, v171
	v_pk_mul_f32 v[84:85], v[84:85], v[88:89]
	v_pk_mul_f32 v[82:83], v[82:83], v[86:87]
	v_lshlrev_b32_e32 v86, 16, v172
	v_and_b32_e32 v87, 0xffff0000, v172
	v_lshlrev_b32_e32 v88, 16, v173
	v_and_b32_e32 v89, 0xffff0000, v173
	v_pk_mul_f32 v[88:89], v[80:81], v[88:89]
	v_pk_mul_f32 v[80:81], v[78:79], v[86:87]
	s_and_b64 vcc, exec, s[2:3]
	s_mov_b64 s[4:5], -1
	v_cvt_pk_bf16_f32 v78, v82, v83
	v_cvt_pk_bf16_f32 v79, v84, v85
	v_cvt_pk_bf16_f32 v80, v80, v81
	v_cvt_pk_bf16_f32 v81, v88, v89
	s_cbranch_vccnz .LBB0_650
	s_mov_b64 s[4:5], 0

.LBB0_652:
	s_nop 1
	s_waitcnt vmcnt(15)
	v_lshlrev_b32_e32 v78, 16, v166
	v_and_b32_e32 v79, 0xffff0000, v166
	v_lshlrev_b32_e32 v80, 16, v167
	v_and_b32_e32 v81, 0xffff0000, v167
	v_pk_mul_f32 v[76:77], v[76:77], v[80:81]
	v_pk_mul_f32 v[74:75], v[74:75], v[78:79]
	v_lshlrev_b32_e32 v78, 16, v168
	v_and_b32_e32 v79, 0xffff0000, v168
	v_lshlrev_b32_e32 v80, 16, v169
	v_and_b32_e32 v81, 0xffff0000, v169
	v_pk_mul_f32 v[80:81], v[72:73], v[80:81]
	v_pk_mul_f32 v[72:73], v[70:71], v[78:79]
	s_and_b64 vcc, exec, s[2:3]
	s_mov_b64 s[4:5], -1
	v_cvt_pk_bf16_f32 v70, v74, v75
	v_cvt_pk_bf16_f32 v71, v76, v77
	v_cvt_pk_bf16_f32 v72, v72, v73
	v_cvt_pk_bf16_f32 v73, v80, v81
	s_cbranch_vccnz .LBB0_654
	s_mov_b64 s[4:5], 0

.LBB0_656:
	s_nop 1
	s_waitcnt vmcnt(15)
	v_lshlrev_b32_e32 v70, 16, v162
	v_and_b32_e32 v71, 0xffff0000, v162
	v_lshlrev_b32_e32 v72, 16, v163
	v_and_b32_e32 v73, 0xffff0000, v163
	v_pk_mul_f32 v[68:69], v[68:69], v[72:73]
	v_pk_mul_f32 v[66:67], v[66:67], v[70:71]
	v_lshlrev_b32_e32 v70, 16, v164
	v_and_b32_e32 v71, 0xffff0000, v164
	v_lshlrev_b32_e32 v72, 16, v165
	v_and_b32_e32 v73, 0xffff0000, v165
	v_pk_mul_f32 v[72:73], v[64:65], v[72:73]
	v_pk_mul_f32 v[64:65], v[62:63], v[70:71]
	s_and_b64 vcc, exec, s[2:3]
	s_mov_b64 s[4:5], -1
	v_cvt_pk_bf16_f32 v62, v66, v67
	v_cvt_pk_bf16_f32 v63, v68, v69
	v_cvt_pk_bf16_f32 v64, v64, v65
	v_cvt_pk_bf16_f32 v65, v72, v73
	s_cbranch_vccnz .LBB0_658
	s_mov_b64 s[4:5], 0

.LBB0_660:
	s_nop 1
	s_waitcnt vmcnt(15)
	v_lshlrev_b32_e32 v62, 16, v158
	v_and_b32_e32 v63, 0xffff0000, v158
	v_lshlrev_b32_e32 v64, 16, v159
	v_and_b32_e32 v65, 0xffff0000, v159
	v_pk_mul_f32 v[60:61], v[60:61], v[64:65]
	v_pk_mul_f32 v[58:59], v[58:59], v[62:63]
	v_lshlrev_b32_e32 v62, 16, v160
	v_and_b32_e32 v63, 0xffff0000, v160
	v_lshlrev_b32_e32 v64, 16, v161
	v_and_b32_e32 v65, 0xffff0000, v161
	v_pk_mul_f32 v[64:65], v[56:57], v[64:65]
	v_pk_mul_f32 v[56:57], v[54:55], v[62:63]
	s_and_b64 vcc, exec, s[2:3]
	s_mov_b64 s[4:5], -1
	v_cvt_pk_bf16_f32 v54, v58, v59
	v_cvt_pk_bf16_f32 v55, v60, v61
	v_cvt_pk_bf16_f32 v56, v56, v57
	v_cvt_pk_bf16_f32 v57, v64, v65
	s_cbranch_vccnz .LBB0_662
	s_mov_b64 s[4:5], 0

.LBB0_664:
	s_nop 1
	s_waitcnt vmcnt(15)
	v_lshlrev_b32_e32 v54, 16, v154
	v_and_b32_e32 v55, 0xffff0000, v154
	v_lshlrev_b32_e32 v56, 16, v155
	v_and_b32_e32 v57, 0xffff0000, v155
	v_pk_mul_f32 v[52:53], v[52:53], v[56:57]
	v_pk_mul_f32 v[50:51], v[50:51], v[54:55]
	v_lshlrev_b32_e32 v54, 16, v156
	v_and_b32_e32 v55, 0xffff0000, v156
	v_lshlrev_b32_e32 v56, 16, v157
	v_and_b32_e32 v57, 0xffff0000, v157
	v_pk_mul_f32 v[56:57], v[48:49], v[56:57]
	v_pk_mul_f32 v[48:49], v[46:47], v[54:55]
	s_and_b64 vcc, exec, s[2:3]
	s_mov_b64 s[4:5], -1
	v_cvt_pk_bf16_f32 v46, v50, v51
	v_cvt_pk_bf16_f32 v47, v52, v53
	v_cvt_pk_bf16_f32 v48, v48, v49
	v_cvt_pk_bf16_f32 v49, v56, v57
	s_cbranch_vccnz .LBB0_666
	s_mov_b64 s[4:5], 0

.LBB0_668:
	s_nop 1
	s_waitcnt vmcnt(15)
	v_lshlrev_b32_e32 v46, 16, v150
	v_and_b32_e32 v47, 0xffff0000, v150
	v_lshlrev_b32_e32 v48, 16, v151
	v_and_b32_e32 v49, 0xffff0000, v151
	v_pk_mul_f32 v[44:45], v[44:45], v[48:49]
	v_pk_mul_f32 v[42:43], v[42:43], v[46:47]
	v_lshlrev_b32_e32 v46, 16, v152
	v_and_b32_e32 v47, 0xffff0000, v152
	v_lshlrev_b32_e32 v48, 16, v153
	v_and_b32_e32 v49, 0xffff0000, v153
	v_pk_mul_f32 v[48:49], v[40:41], v[48:49]
	v_pk_mul_f32 v[40:41], v[38:39], v[46:47]
	s_and_b64 vcc, exec, s[2:3]
	s_mov_b64 s[4:5], -1
	v_cvt_pk_bf16_f32 v38, v42, v43
	v_cvt_pk_bf16_f32 v39, v44, v45
	v_cvt_pk_bf16_f32 v40, v40, v41
	v_cvt_pk_bf16_f32 v41, v48, v49
	s_cbranch_vccnz .LBB0_670
	s_mov_b64 s[4:5], 0

.LBB0_672:
	s_nop 1
	s_waitcnt vmcnt(15)
	v_lshlrev_b32_e32 v38, 16, v146
	v_and_b32_e32 v39, 0xffff0000, v146
	v_lshlrev_b32_e32 v40, 16, v147
	v_and_b32_e32 v41, 0xffff0000, v147
	v_pk_mul_f32 v[36:37], v[36:37], v[40:41]
	v_pk_mul_f32 v[34:35], v[34:35], v[38:39]
	v_lshlrev_b32_e32 v38, 16, v148
	v_and_b32_e32 v39, 0xffff0000, v148
	v_lshlrev_b32_e32 v40, 16, v149
	v_and_b32_e32 v41, 0xffff0000, v149
	v_pk_mul_f32 v[40:41], v[32:33], v[40:41]
	v_pk_mul_f32 v[32:33], v[30:31], v[38:39]
	s_and_b64 vcc, exec, s[2:3]
	s_mov_b64 s[4:5], -1
	v_cvt_pk_bf16_f32 v30, v34, v35
	v_cvt_pk_bf16_f32 v31, v36, v37
	v_cvt_pk_bf16_f32 v32, v32, v33
	v_cvt_pk_bf16_f32 v33, v40, v41
	s_cbranch_vccnz .LBB0_674
	s_mov_b64 s[4:5], 0

.LBB0_676:
	s_nop 1
	s_waitcnt vmcnt(15)
	v_lshlrev_b32_e32 v30, 16, v142
	v_and_b32_e32 v31, 0xffff0000, v142
	v_lshlrev_b32_e32 v32, 16, v143
	v_and_b32_e32 v33, 0xffff0000, v143
	v_pk_mul_f32 v[28:29], v[28:29], v[32:33]
	v_pk_mul_f32 v[26:27], v[26:27], v[30:31]
	v_lshlrev_b32_e32 v30, 16, v144
	v_and_b32_e32 v31, 0xffff0000, v144
	v_lshlrev_b32_e32 v32, 16, v145
	v_and_b32_e32 v33, 0xffff0000, v145
	v_pk_mul_f32 v[32:33], v[24:25], v[32:33]
	v_pk_mul_f32 v[24:25], v[22:23], v[30:31]
	s_and_b64 vcc, exec, s[2:3]
	s_mov_b64 s[4:5], -1
	v_cvt_pk_bf16_f32 v22, v26, v27
	v_cvt_pk_bf16_f32 v23, v28, v29
	v_cvt_pk_bf16_f32 v24, v24, v25
	v_cvt_pk_bf16_f32 v25, v32, v33
	s_cbranch_vccnz .LBB0_678
	s_mov_b64 s[4:5], 0

.LBB0_680:
	s_nop 1
	s_waitcnt vmcnt(15)
	v_lshlrev_b32_e32 v22, 16, v138
	v_and_b32_e32 v23, 0xffff0000, v138
	v_lshlrev_b32_e32 v24, 16, v139
	v_and_b32_e32 v25, 0xffff0000, v139
	v_pk_mul_f32 v[20:21], v[20:21], v[24:25]
	v_pk_mul_f32 v[18:19], v[18:19], v[22:23]
	v_lshlrev_b32_e32 v22, 16, v140
	v_and_b32_e32 v23, 0xffff0000, v140
	v_lshlrev_b32_e32 v24, 16, v141
	v_and_b32_e32 v25, 0xffff0000, v141
	v_pk_mul_f32 v[24:25], v[16:17], v[24:25]
	v_pk_mul_f32 v[16:17], v[14:15], v[22:23]
	s_and_b64 vcc, exec, s[2:3]
	s_mov_b64 s[4:5], -1
	v_cvt_pk_bf16_f32 v14, v18, v19
	v_cvt_pk_bf16_f32 v15, v20, v21
	v_cvt_pk_bf16_f32 v16, v16, v17
	v_cvt_pk_bf16_f32 v17, v24, v25
	s_cbranch_vccnz .LBB0_682
	s_mov_b64 s[4:5], 0

.LBB0_684:
	s_waitcnt vmcnt(15)
	v_lshlrev_b32_e32 v4, 16, v134
	v_and_b32_e32 v5, 0xffff0000, v134
	v_lshlrev_b32_e32 v14, 16, v135
	v_and_b32_e32 v15, 0xffff0000, v135
	v_pk_mul_f32 v[4:5], v[10:11], v[4:5]
	v_lshlrev_b32_e32 v10, 16, v136
	v_and_b32_e32 v11, 0xffff0000, v136
	v_pk_mul_f32 v[12:13], v[12:13], v[14:15]
	v_lshlrev_b32_e32 v14, 16, v137
	v_and_b32_e32 v15, 0xffff0000, v137
	v_pk_mul_f32 v[6:7], v[6:7], v[10:11]
	s_and_b64 vcc, exec, s[2:3]
	s_mov_b64 s[2:3], -1
	v_pk_mul_f32 v[8:9], v[8:9], v[14:15]
	v_cvt_pk_bf16_f32 v4, v4, v5
	v_cvt_pk_bf16_f32 v5, v12, v13
	v_cvt_pk_bf16_f32 v6, v6, v7
	s_nop 0
	v_cvt_pk_bf16_f32 v7, v8, v9
	s_cbranch_vccz .LBB0_687
	s_andn2_b64 vcc, exec, s[2:3]
	s_cbranch_vccz .LBB0_688

.LBB0_795:
	s_waitcnt vmcnt(15)
	v_lshlrev_b32_e32 v226, 16, v190
	v_and_b32_e32 v227, 0xffff0000, v190
	v_lshlrev_b32_e32 v190, 16, v191
	v_and_b32_e32 v191, 0xffff0000, v191
	v_pk_add_f32 v[144:145], v[144:145], v[190:191]
	v_pk_add_f32 v[190:191], v[142:143], v[226:227]
	v_lshlrev_b32_e32 v226, 16, v192
	v_and_b32_e32 v227, 0xffff0000, v192
	v_lshlrev_b32_e32 v142, 16, v193
	v_and_b32_e32 v143, 0xffff0000, v193
	v_pk_add_f32 v[142:143], v[136:137], v[142:143]
	v_pk_add_f32 v[192:193], v[134:135], v[226:227]
	s_mov_b64 s[2:3], -1
	s_and_b64 vcc, exec, s[14:15]
	v_cvt_pk_bf16_f32 v134, v190, v191
	v_cvt_pk_bf16_f32 v135, v144, v145
	v_cvt_pk_bf16_f32 v136, v192, v193
	v_cvt_pk_bf16_f32 v137, v142, v143
	s_cbranch_vccz .LBB0_797
	s_mov_b64 s[2:3], 0

.LBB0_799:
	s_nop 1
	s_waitcnt vmcnt(15)
	v_lshlrev_b32_e32 v134, 16, v186
	v_and_b32_e32 v135, 0xffff0000, v186
	v_lshlrev_b32_e32 v136, 16, v187
	v_and_b32_e32 v137, 0xffff0000, v187
	v_pk_add_f32 v[128:129], v[128:129], v[136:137]
	v_pk_add_f32 v[134:135], v[126:127], v[134:135]
	v_lshlrev_b32_e32 v136, 16, v188
	v_and_b32_e32 v137, 0xffff0000, v188
	v_lshlrev_b32_e32 v126, 16, v189
	v_and_b32_e32 v127, 0xffff0000, v189
	v_cndmask_b32_e64 v186, 0, 1, s[14:15]
	v_pk_add_f32 v[126:127], v[124:125], v[126:127]
	v_pk_add_f32 v[136:137], v[122:123], v[136:137]
	v_cmp_ne_u32_e64 s[2:3], 1, v186
	s_andn2_b64 vcc, exec, s[14:15]
	s_mov_b64 s[26:27], -1
	v_cvt_pk_bf16_f32 v122, v134, v135
	v_cvt_pk_bf16_f32 v123, v128, v129
	v_cvt_pk_bf16_f32 v124, v136, v137
	v_cvt_pk_bf16_f32 v125, v126, v127
	s_cbranch_vccnz .LBB0_801
	s_mov_b64 s[26:27], 0

.LBB0_805:
	s_or_b64 exec, exec, s[26:27]
	s_waitcnt vmcnt(16)
	v_lshlrev_b32_e32 v124, 16, v182
	s_waitcnt lgkmcnt(0)
	v_and_b32_e32 v125, 0xffff0000, v182
	v_lshlrev_b32_e32 v126, 16, v183
	v_and_b32_e32 v127, 0xffff0000, v183
	v_pk_add_f32 v[112:113], v[112:113], v[126:127]
	v_pk_add_f32 v[124:125], v[110:111], v[124:125]
	v_lshlrev_b32_e32 v126, 16, v184
	v_and_b32_e32 v127, 0xffff0000, v184
	v_lshlrev_b32_e32 v110, 16, v185
	v_and_b32_e32 v111, 0xffff0000, v185
	v_pk_add_f32 v[110:111], v[108:109], v[110:111]
	v_pk_add_f32 v[126:127], v[106:107], v[126:127]
	s_and_b64 vcc, exec, s[2:3]
	s_mov_b64 s[26:27], -1
	v_cvt_pk_bf16_f32 v106, v124, v125
	v_cvt_pk_bf16_f32 v107, v112, v113
	v_cvt_pk_bf16_f32 v108, v126, v127
	v_cvt_pk_bf16_f32 v109, v110, v111
	s_cbranch_vccnz .LBB0_807
	s_mov_b64 s[26:27], 0

.LBB0_809:
	s_nop 1
	s_waitcnt vmcnt(16)
	v_lshlrev_b32_e32 v106, 16, v178
	v_and_b32_e32 v107, 0xffff0000, v178
	v_lshlrev_b32_e32 v108, 16, v179
	v_and_b32_e32 v109, 0xffff0000, v179
	v_pk_add_f32 v[104:105], v[104:105], v[108:109]
	v_pk_add_f32 v[106:107], v[102:103], v[106:107]
	v_lshlrev_b32_e32 v108, 16, v180
	v_and_b32_e32 v109, 0xffff0000, v180
	v_lshlrev_b32_e32 v102, 16, v181
	v_and_b32_e32 v103, 0xffff0000, v181
	v_pk_add_f32 v[102:103], v[100:101], v[102:103]
	v_pk_add_f32 v[108:109], v[98:99], v[108:109]
	s_and_b64 vcc, exec, s[2:3]
	s_mov_b64 s[26:27], -1
	v_cvt_pk_bf16_f32 v98, v106, v107
	v_cvt_pk_bf16_f32 v99, v104, v105
	v_cvt_pk_bf16_f32 v100, v108, v109
	v_cvt_pk_bf16_f32 v101, v102, v103
	s_cbranch_vccnz .LBB0_811
	s_mov_b64 s[26:27], 0

.LBB0_815:
	s_or_b64 exec, exec, s[26:27]
	s_waitcnt vmcnt(17)
	v_lshlrev_b32_e32 v98, 16, v174
	s_waitcnt lgkmcnt(0)
	v_and_b32_e32 v99, 0xffff0000, v174
	v_lshlrev_b32_e32 v100, 16, v175
	v_and_b32_e32 v101, 0xffff0000, v175
	v_pk_add_f32 v[96:97], v[96:97], v[100:101]
	v_pk_add_f32 v[98:99], v[94:95], v[98:99]
	v_lshlrev_b32_e32 v100, 16, v176
	v_and_b32_e32 v101, 0xffff0000, v176
	v_lshlrev_b32_e32 v94, 16, v177
	v_and_b32_e32 v95, 0xffff0000, v177
	v_pk_add_f32 v[94:95], v[92:93], v[94:95]
	v_pk_add_f32 v[100:101], v[90:91], v[100:101]
	s_and_b64 vcc, exec, s[2:3]
	s_mov_b64 s[26:27], -1
	v_cvt_pk_bf16_f32 v90, v98, v99
	v_cvt_pk_bf16_f32 v91, v96, v97
	v_cvt_pk_bf16_f32 v92, v100, v101
	v_cvt_pk_bf16_f32 v93, v94, v95
	s_cbranch_vccnz .LBB0_817
	s_mov_b64 s[26:27], 0

.LBB0_819:
	s_nop 1
	s_waitcnt vmcnt(17)
	v_lshlrev_b32_e32 v90, 16, v170
	v_and_b32_e32 v91, 0xffff0000, v170
	v_lshlrev_b32_e32 v92, 16, v171
	v_and_b32_e32 v93, 0xffff0000, v171
	v_pk_add_f32 v[88:89], v[88:89], v[92:93]
	v_pk_add_f32 v[90:91], v[86:87], v[90:91]
	v_lshlrev_b32_e32 v92, 16, v172
	v_and_b32_e32 v93, 0xffff0000, v172
	v_lshlrev_b32_e32 v86, 16, v173
	v_and_b32_e32 v87, 0xffff0000, v173
	v_pk_add_f32 v[86:87], v[84:85], v[86:87]
	v_pk_add_f32 v[92:93], v[82:83], v[92:93]
	s_and_b64 vcc, exec, s[2:3]
	s_mov_b64 s[26:27], -1
	v_cvt_pk_bf16_f32 v82, v90, v91
	v_cvt_pk_bf16_f32 v83, v88, v89
	v_cvt_pk_bf16_f32 v84, v92, v93
	v_cvt_pk_bf16_f32 v85, v86, v87
	s_cbranch_vccnz .LBB0_821
	s_mov_b64 s[26:27], 0

.LBB0_825:
	s_or_b64 exec, exec, s[26:27]
	s_waitcnt vmcnt(18)
	v_lshlrev_b32_e32 v82, 16, v166
	s_waitcnt lgkmcnt(0)
	v_and_b32_e32 v83, 0xffff0000, v166
	v_lshlrev_b32_e32 v84, 16, v167
	v_and_b32_e32 v85, 0xffff0000, v167
	v_pk_add_f32 v[80:81], v[80:81], v[84:85]
	v_pk_add_f32 v[82:83], v[78:79], v[82:83]
	v_lshlrev_b32_e32 v84, 16, v168
	v_and_b32_e32 v85, 0xffff0000, v168
	v_lshlrev_b32_e32 v78, 16, v169
	v_and_b32_e32 v79, 0xffff0000, v169
	v_pk_add_f32 v[78:79], v[76:77], v[78:79]
	v_pk_add_f32 v[84:85], v[74:75], v[84:85]
	s_and_b64 vcc, exec, s[2:3]
	s_mov_b64 s[26:27], -1
	v_cvt_pk_bf16_f32 v74, v82, v83
	v_cvt_pk_bf16_f32 v75, v80, v81
	v_cvt_pk_bf16_f32 v76, v84, v85
	v_cvt_pk_bf16_f32 v77, v78, v79
	s_cbranch_vccnz .LBB0_827
	s_mov_b64 s[26:27], 0

.LBB0_829:
	s_nop 1
	s_waitcnt vmcnt(18)
	v_lshlrev_b32_e32 v74, 16, v162
	v_and_b32_e32 v75, 0xffff0000, v162
	v_lshlrev_b32_e32 v76, 16, v163
	v_and_b32_e32 v77, 0xffff0000, v163
	v_pk_add_f32 v[72:73], v[72:73], v[76:77]
	v_pk_add_f32 v[74:75], v[70:71], v[74:75]
	v_lshlrev_b32_e32 v76, 16, v164
	v_and_b32_e32 v77, 0xffff0000, v164
	v_lshlrev_b32_e32 v70, 16, v165
	v_and_b32_e32 v71, 0xffff0000, v165
	v_pk_add_f32 v[70:71], v[68:69], v[70:71]
	v_pk_add_f32 v[76:77], v[66:67], v[76:77]
	s_and_b64 vcc, exec, s[2:3]
	s_mov_b64 s[26:27], -1
	v_cvt_pk_bf16_f32 v66, v74, v75
	v_cvt_pk_bf16_f32 v67, v72, v73
	v_cvt_pk_bf16_f32 v68, v76, v77
	v_cvt_pk_bf16_f32 v69, v70, v71
	s_cbranch_vccnz .LBB0_831
	s_mov_b64 s[26:27], 0

.LBB0_835:
	s_or_b64 exec, exec, s[26:27]
	s_waitcnt vmcnt(19)
	v_lshlrev_b32_e32 v66, 16, v158
	s_waitcnt lgkmcnt(0)
	v_and_b32_e32 v67, 0xffff0000, v158
	v_lshlrev_b32_e32 v68, 16, v159
	v_and_b32_e32 v69, 0xffff0000, v159
	v_pk_add_f32 v[64:65], v[64:65], v[68:69]
	v_pk_add_f32 v[66:67], v[62:63], v[66:67]
	v_lshlrev_b32_e32 v68, 16, v160
	v_and_b32_e32 v69, 0xffff0000, v160
	v_lshlrev_b32_e32 v62, 16, v161
	v_and_b32_e32 v63, 0xffff0000, v161
	v_pk_add_f32 v[62:63], v[60:61], v[62:63]
	v_pk_add_f32 v[68:69], v[58:59], v[68:69]
	s_and_b64 vcc, exec, s[2:3]
	s_mov_b64 s[26:27], -1
	v_cvt_pk_bf16_f32 v58, v66, v67
	v_cvt_pk_bf16_f32 v59, v64, v65
	v_cvt_pk_bf16_f32 v60, v68, v69
	v_cvt_pk_bf16_f32 v61, v62, v63
	s_cbranch_vccnz .LBB0_837
	s_mov_b64 s[26:27], 0

.LBB0_839:
	s_nop 1
	s_waitcnt vmcnt(19)
	v_lshlrev_b32_e32 v58, 16, v154
	v_and_b32_e32 v59, 0xffff0000, v154
	v_lshlrev_b32_e32 v60, 16, v155
	v_and_b32_e32 v61, 0xffff0000, v155
	v_pk_add_f32 v[56:57], v[56:57], v[60:61]
	v_pk_add_f32 v[58:59], v[54:55], v[58:59]
	v_lshlrev_b32_e32 v60, 16, v156
	v_and_b32_e32 v61, 0xffff0000, v156
	v_lshlrev_b32_e32 v54, 16, v157
	v_and_b32_e32 v55, 0xffff0000, v157
	v_pk_add_f32 v[54:55], v[52:53], v[54:55]
	v_pk_add_f32 v[60:61], v[50:51], v[60:61]
	s_and_b64 vcc, exec, s[2:3]
	s_mov_b64 s[26:27], -1
	v_cvt_pk_bf16_f32 v50, v58, v59
	v_cvt_pk_bf16_f32 v51, v56, v57
	v_cvt_pk_bf16_f32 v52, v60, v61
	v_cvt_pk_bf16_f32 v53, v54, v55
	s_cbranch_vccnz .LBB0_841
	s_mov_b64 s[26:27], 0

.LBB0_845:
	s_or_b64 exec, exec, s[26:27]
	s_waitcnt vmcnt(20)
	v_lshlrev_b32_e32 v50, 16, v150
	s_waitcnt lgkmcnt(0)
	v_and_b32_e32 v51, 0xffff0000, v150
	v_lshlrev_b32_e32 v52, 16, v151
	v_and_b32_e32 v53, 0xffff0000, v151
	v_pk_add_f32 v[48:49], v[48:49], v[52:53]
	v_pk_add_f32 v[50:51], v[46:47], v[50:51]
	v_lshlrev_b32_e32 v52, 16, v152
	v_and_b32_e32 v53, 0xffff0000, v152
	v_lshlrev_b32_e32 v46, 16, v153
	v_and_b32_e32 v47, 0xffff0000, v153
	v_pk_add_f32 v[46:47], v[44:45], v[46:47]
	v_pk_add_f32 v[52:53], v[42:43], v[52:53]
	s_and_b64 vcc, exec, s[2:3]
	s_mov_b64 s[26:27], -1
	v_cvt_pk_bf16_f32 v42, v50, v51
	v_cvt_pk_bf16_f32 v43, v48, v49
	v_cvt_pk_bf16_f32 v44, v52, v53
	v_cvt_pk_bf16_f32 v45, v46, v47
	s_cbranch_vccnz .LBB0_847
	s_mov_b64 s[26:27], 0

.LBB0_849:
	s_nop 1
	s_waitcnt vmcnt(20)
	v_lshlrev_b32_e32 v42, 16, v146
	v_and_b32_e32 v43, 0xffff0000, v146
	v_lshlrev_b32_e32 v44, 16, v147
	v_and_b32_e32 v45, 0xffff0000, v147
	v_pk_add_f32 v[40:41], v[40:41], v[44:45]
	v_pk_add_f32 v[42:43], v[38:39], v[42:43]
	v_lshlrev_b32_e32 v44, 16, v148
	v_and_b32_e32 v45, 0xffff0000, v148
	v_lshlrev_b32_e32 v38, 16, v149
	v_and_b32_e32 v39, 0xffff0000, v149
	v_pk_add_f32 v[38:39], v[36:37], v[38:39]
	v_pk_add_f32 v[44:45], v[34:35], v[44:45]
	s_and_b64 vcc, exec, s[2:3]
	s_mov_b64 s[26:27], -1
	v_cvt_pk_bf16_f32 v34, v42, v43
	v_cvt_pk_bf16_f32 v35, v40, v41
	v_cvt_pk_bf16_f32 v36, v44, v45
	v_cvt_pk_bf16_f32 v37, v38, v39
	s_cbranch_vccnz .LBB0_851
	s_mov_b64 s[26:27], 0

.LBB0_855:
	s_or_b64 exec, exec, s[26:27]
	s_waitcnt vmcnt(21)
	v_lshlrev_b32_e32 v34, 16, v138
	s_waitcnt lgkmcnt(0)
	v_and_b32_e32 v35, 0xffff0000, v138
	v_lshlrev_b32_e32 v36, 16, v139
	v_and_b32_e32 v37, 0xffff0000, v139
	v_pk_add_f32 v[32:33], v[32:33], v[36:37]
	v_pk_add_f32 v[34:35], v[30:31], v[34:35]
	v_lshlrev_b32_e32 v36, 16, v140
	v_and_b32_e32 v37, 0xffff0000, v140
	v_lshlrev_b32_e32 v30, 16, v141
	v_and_b32_e32 v31, 0xffff0000, v141
	v_pk_add_f32 v[30:31], v[28:29], v[30:31]
	v_pk_add_f32 v[36:37], v[26:27], v[36:37]
	s_and_b64 vcc, exec, s[2:3]
	s_mov_b64 s[26:27], -1
	v_cvt_pk_bf16_f32 v26, v34, v35
	v_cvt_pk_bf16_f32 v27, v32, v33
	v_cvt_pk_bf16_f32 v28, v36, v37
	v_cvt_pk_bf16_f32 v29, v30, v31
	s_cbranch_vccnz .LBB0_857
	s_mov_b64 s[26:27], 0

.LBB0_859:
	s_nop 1
	s_waitcnt vmcnt(21)
	v_lshlrev_b32_e32 v26, 16, v130
	v_and_b32_e32 v27, 0xffff0000, v130
	v_lshlrev_b32_e32 v28, 16, v131
	v_and_b32_e32 v29, 0xffff0000, v131
	v_pk_add_f32 v[24:25], v[24:25], v[28:29]
	v_pk_add_f32 v[26:27], v[22:23], v[26:27]
	v_lshlrev_b32_e32 v28, 16, v132
	v_and_b32_e32 v29, 0xffff0000, v132
	v_lshlrev_b32_e32 v22, 16, v133
	v_and_b32_e32 v23, 0xffff0000, v133
	v_pk_add_f32 v[22:23], v[20:21], v[22:23]
	v_pk_add_f32 v[28:29], v[18:19], v[28:29]
	s_and_b64 vcc, exec, s[2:3]
	s_mov_b64 s[26:27], -1
	v_cvt_pk_bf16_f32 v18, v26, v27
	v_cvt_pk_bf16_f32 v19, v24, v25
	v_cvt_pk_bf16_f32 v20, v28, v29
	v_cvt_pk_bf16_f32 v21, v22, v23
	s_cbranch_vccnz .LBB0_861
	s_mov_b64 s[26:27], 0

.LBB0_865:
	s_or_b64 exec, exec, s[26:27]
	s_waitcnt vmcnt(22)
	v_lshlrev_b32_e32 v18, 16, v118
	s_waitcnt lgkmcnt(0)
	v_and_b32_e32 v19, 0xffff0000, v118
	v_lshlrev_b32_e32 v20, 16, v119
	v_and_b32_e32 v21, 0xffff0000, v119
	v_pk_add_f32 v[16:17], v[16:17], v[20:21]
	v_pk_add_f32 v[18:19], v[14:15], v[18:19]
	v_lshlrev_b32_e32 v20, 16, v120
	v_and_b32_e32 v21, 0xffff0000, v120
	v_lshlrev_b32_e32 v14, 16, v121
	v_and_b32_e32 v15, 0xffff0000, v121
	v_pk_add_f32 v[14:15], v[12:13], v[14:15]
	v_pk_add_f32 v[20:21], v[10:11], v[20:21]
	s_and_b64 vcc, exec, s[2:3]
	s_mov_b64 s[26:27], -1
	v_cvt_pk_bf16_f32 v10, v18, v19
	v_cvt_pk_bf16_f32 v11, v16, v17
	v_cvt_pk_bf16_f32 v12, v20, v21
	v_cvt_pk_bf16_f32 v13, v14, v15
	s_cbranch_vccnz .LBB0_867
	s_mov_b64 s[26:27], 0

.LBB0_869:
	s_nop 1
	s_waitcnt vmcnt(22)
	v_lshlrev_b32_e32 v10, 16, v114
	v_and_b32_e32 v11, 0xffff0000, v114
	v_lshlrev_b32_e32 v12, 16, v115
	v_and_b32_e32 v13, 0xffff0000, v115
	v_pk_add_f32 v[8:9], v[8:9], v[12:13]
	v_pk_add_f32 v[10:11], v[6:7], v[10:11]
	v_lshlrev_b32_e32 v12, 16, v116
	v_and_b32_e32 v13, 0xffff0000, v116
	v_lshlrev_b32_e32 v6, 16, v117
	v_and_b32_e32 v7, 0xffff0000, v117
	v_pk_add_f32 v[6:7], v[4:5], v[6:7]
	v_pk_add_f32 v[12:13], v[2:3], v[12:13]
	s_and_b64 vcc, exec, s[2:3]
	s_mov_b64 s[2:3], -1
	v_cvt_pk_bf16_f32 v2, v10, v11
	v_cvt_pk_bf16_f32 v3, v8, v9
	v_cvt_pk_bf16_f32 v4, v12, v13
	v_cvt_pk_bf16_f32 v5, v6, v7
	s_cbranch_vccnz .LBB0_871
	s_mov_b64 s[2:3], 0

.LBB0_1021:
	s_lshl_b32 s2, s37, 8
	s_lshl_b32 s0, s38, 5
	v_add_u32_e32 v134, s2, v210
	s_or_b32 s0, s0, s41
	v_lshrrev_b32_e32 v130, 2, v211
	v_ashrrev_i32_e32 v135, 31, v134
	v_and_or_b32 v216, v130, 12, s0
	v_lshlrev_b64 v[136:137], 11, v[134:135]
	v_lshl_add_u64 v[136:137], s[64:65], 0, v[136:137]
	v_lshlrev_b32_e32 v130, 1, v216
	v_lshl_add_u64 v[136:137], v[136:137], 0, v[130:131]
	s_barrier
	global_load_dword v214, v131, s[70:71] sc1
	global_load_dword v215, v131, s[10:11] sc1
	global_load_dword v213, v131, s[12:13] sc1
	global_load_dwordx2 v[218:219], v[136:137], off
	global_load_dwordx2 v[220:221], v[136:137], off offset:32
	global_load_dwordx2 v[222:223], v[136:137], off offset:256
	global_load_dwordx2 v[224:225], v[136:137], off offset:288
	v_add_u32_e32 v136, 16, v134
	v_ashrrev_i32_e32 v137, 31, v136
	v_lshlrev_b64 v[138:139], 11, v[136:137]
	v_lshl_add_u64 v[138:139], s[64:65], 0, v[138:139]
	v_lshl_add_u64 v[138:139], v[138:139], 0, v[130:131]
	global_load_dwordx2 v[204:205], v[138:139], off
	global_load_dwordx2 v[202:203], v[138:139], off offset:32
	global_load_dwordx2 v[200:201], v[138:139], off offset:256
	global_load_dwordx2 v[198:199], v[138:139], off offset:288
	v_add_u32_e32 v138, 32, v134
	v_ashrrev_i32_e32 v139, 31, v138
	v_lshlrev_b64 v[140:141], 11, v[138:139]
	v_lshl_add_u64 v[140:141], s[64:65], 0, v[140:141]
	v_lshl_add_u64 v[140:141], v[140:141], 0, v[130:131]
	global_load_dwordx2 v[196:197], v[140:141], off
	global_load_dwordx2 v[194:195], v[140:141], off offset:32
	global_load_dwordx2 v[192:193], v[140:141], off offset:256
	global_load_dwordx2 v[190:191], v[140:141], off offset:288
	v_add_u32_e32 v140, 48, v134
	v_ashrrev_i32_e32 v141, 31, v140
	v_lshlrev_b64 v[142:143], 11, v[140:141]
	v_lshl_add_u64 v[142:143], s[64:65], 0, v[142:143]
	v_lshl_add_u64 v[142:143], v[142:143], 0, v[130:131]
	global_load_dwordx2 v[188:189], v[142:143], off
	global_load_dwordx2 v[186:187], v[142:143], off offset:32
	global_load_dwordx2 v[184:185], v[142:143], off offset:256
	global_load_dwordx2 v[182:183], v[142:143], off offset:288
	v_add_u32_e32 v142, 0x80, v134
	v_ashrrev_i32_e32 v143, 31, v142
	v_lshlrev_b64 v[144:145], 11, v[142:143]
	v_lshl_add_u64 v[144:145], s[64:65], 0, v[144:145]
	v_lshl_add_u64 v[144:145], v[144:145], 0, v[130:131]
	global_load_dwordx2 v[180:181], v[144:145], off
	global_load_dwordx2 v[178:179], v[144:145], off offset:32
	global_load_dwordx2 v[176:177], v[144:145], off offset:256
	global_load_dwordx2 v[174:175], v[144:145], off offset:288
	v_add_u32_e32 v144, 0x90, v134
	v_ashrrev_i32_e32 v145, 31, v144
	v_lshlrev_b64 v[146:147], 11, v[144:145]
	v_lshl_add_u64 v[146:147], s[64:65], 0, v[146:147]
	v_lshl_add_u64 v[146:147], v[146:147], 0, v[130:131]
	global_load_dwordx2 v[172:173], v[146:147], off
	global_load_dwordx2 v[170:171], v[146:147], off offset:32
	global_load_dwordx2 v[168:169], v[146:147], off offset:256
	global_load_dwordx2 v[166:167], v[146:147], off offset:288
	v_add_u32_e32 v146, 0xa0, v134
	v_ashrrev_i32_e32 v147, 31, v146
	v_lshlrev_b64 v[148:149], 11, v[146:147]
	v_lshl_add_u64 v[148:149], s[64:65], 0, v[148:149]
	v_lshl_add_u64 v[148:149], v[148:149], 0, v[130:131]
	global_load_dwordx2 v[164:165], v[148:149], off
	global_load_dwordx2 v[162:163], v[148:149], off offset:32
	global_load_dwordx2 v[160:161], v[148:149], off offset:256
	global_load_dwordx2 v[158:159], v[148:149], off offset:288
	v_add_u32_e32 v148, 0xb0, v134
	v_ashrrev_i32_e32 v149, 31, v148
	v_lshlrev_b64 v[150:151], 11, v[148:149]
	v_lshl_add_u64 v[150:151], s[64:65], 0, v[150:151]
	v_lshl_add_u64 v[150:151], v[150:151], 0, v[130:131]
	global_load_dwordx2 v[156:157], v[150:151], off
	global_load_dwordx2 v[154:155], v[150:151], off offset:32
	global_load_dwordx2 v[152:153], v[150:151], off offset:256
	s_nop 0
	global_load_dwordx2 v[150:151], v[150:151], off offset:288
	v_and_b32_e32 v217, 64, v1
	v_xor_b32_e32 v130, 16, v1
	s_lshl_b32 s0, s38, 2
	s_add_i32 s3, s0, 0
	s_waitcnt vmcnt(31)
	v_lshlrev_b32_e32 v226, 16, v218
	v_and_b32_e32 v227, 0xffff0000, v218
	v_lshlrev_b32_e32 v218, 16, v219
	v_and_b32_e32 v219, 0xffff0000, v219
	v_pk_add_f32 v[128:129], v[128:129], v[218:219]
	s_waitcnt vmcnt(30)
	v_lshlrev_b32_e32 v218, 16, v220
	v_and_b32_e32 v219, 0xffff0000, v220
	v_pk_add_f32 v[122:123], v[122:123], v[218:219]
	s_waitcnt vmcnt(29)
	v_lshlrev_b32_e32 v218, 16, v222
	v_and_b32_e32 v219, 0xffff0000, v222
	v_pk_add_f32 v[118:119], v[118:119], v[218:219]
	s_waitcnt vmcnt(28)
	v_lshlrev_b32_e32 v218, 16, v224
	v_and_b32_e32 v219, 0xffff0000, v224
	v_pk_add_f32 v[114:115], v[114:115], v[218:219]
	v_add_u32_e32 v218, 64, v217
	v_cmp_lt_i32_e32 vcc, v130, v218
	v_pk_add_f32 v[126:127], v[126:127], v[226:227]
	v_lshlrev_b32_e32 v220, 16, v221
	v_and_b32_e32 v221, 0xffff0000, v221
	v_cndmask_b32_e32 v130, v1, v130, vcc
	v_pk_add_f32 v[124:125], v[124:125], v[220:221]
	v_lshlrev_b32_e32 v220, 16, v223
	v_and_b32_e32 v221, 0xffff0000, v223
	v_lshlrev_b32_e32 v217, 2, v130
	v_mul_f32_e32 v130, v127, v127
	v_mul_f32_e32 v219, v129, v129
	v_pk_add_f32 v[120:121], v[120:121], v[220:221]
	v_lshlrev_b32_e32 v220, 16, v225
	v_and_b32_e32 v221, 0xffff0000, v225
	v_fmac_f32_e32 v130, v126, v126
	v_fmac_f32_e32 v219, v128, v128
	v_pk_add_f32 v[116:117], v[116:117], v[220:221]
	v_add_f32_e32 v130, v130, v219
	v_mul_f32_e32 v219, v123, v123
	v_mul_f32_e32 v220, v125, v125
	v_fmac_f32_e32 v219, v122, v122
	v_fmac_f32_e32 v220, v124, v124
	v_add_f32_e32 v219, v219, v220
	v_add_f32_e32 v130, v130, v219
	v_mul_f32_e32 v219, v119, v119
	v_mul_f32_e32 v220, v121, v121
	v_fmac_f32_e32 v219, v118, v118
	v_fmac_f32_e32 v220, v120, v120
	v_add_f32_e32 v219, v219, v220
	v_add_f32_e32 v130, v130, v219
	v_mul_f32_e32 v219, v115, v115
	v_mul_f32_e32 v220, v117, v117
	v_fmac_f32_e32 v219, v114, v114
	v_fmac_f32_e32 v220, v116, v116
	v_add_f32_e32 v219, v219, v220
	v_add_f32_e32 v130, v130, v219
	ds_bpermute_b32 v219, v217, v130
	v_xor_b32_e32 v220, 32, v1
	v_cmp_lt_i32_e32 vcc, v220, v218
	s_waitcnt lgkmcnt(0)
	v_add_f32_e32 v219, v130, v219
	v_cndmask_b32_e32 v218, v1, v220, vcc
	v_lshlrev_b32_e32 v218, 2, v218
	ds_bpermute_b32 v220, v218, v219
	v_and_b32_e32 v130, 63, v211
	v_cmp_gt_u32_e32 vcc, 16, v130
	s_and_saveexec_b64 s[0:1], vcc
	s_cbranch_execz .LBB0_1023
	s_lshl_b32 s4, s35, 10
	s_add_i32 s4, s3, s4
	v_lshl_add_u32 v221, v212, 4, s4
	s_waitcnt lgkmcnt(0)
	v_add_f32_e32 v219, v219, v220
	ds_write_b32 v221, v219
.LBB0_1023:
	s_or_b64 exec, exec, s[0:1]
	s_waitcnt lgkmcnt(0)
	s_waitcnt vmcnt(27)
	v_lshlrev_b32_e32 v220, 16, v204
	v_and_b32_e32 v221, 0xffff0000, v204
	v_lshlrev_b32_e32 v204, 16, v205
	v_and_b32_e32 v205, 0xffff0000, v205
	v_pk_add_f32 v[112:113], v[112:113], v[204:205]
	s_waitcnt vmcnt(26)
	v_lshlrev_b32_e32 v204, 16, v202
	v_and_b32_e32 v205, 0xffff0000, v202
	v_lshlrev_b32_e32 v202, 16, v203
	v_and_b32_e32 v203, 0xffff0000, v203
	v_pk_add_f32 v[108:109], v[108:109], v[202:203]
	s_waitcnt vmcnt(25)
	v_lshlrev_b32_e32 v202, 16, v200
	v_and_b32_e32 v203, 0xffff0000, v200
	v_lshlrev_b32_e32 v200, 16, v201
	v_and_b32_e32 v201, 0xffff0000, v201
	v_pk_add_f32 v[110:111], v[110:111], v[220:221]
	v_pk_add_f32 v[104:105], v[104:105], v[200:201]
	s_waitcnt vmcnt(24)
	v_lshlrev_b32_e32 v200, 16, v198
	v_and_b32_e32 v201, 0xffff0000, v198
	v_lshlrev_b32_e32 v198, 16, v199
	v_and_b32_e32 v199, 0xffff0000, v199
	v_pk_add_f32 v[100:101], v[100:101], v[198:199]
	v_mul_f32_e32 v198, v111, v111
	v_mul_f32_e32 v199, v113, v113
	v_pk_add_f32 v[106:107], v[106:107], v[204:205]
	v_fmac_f32_e32 v198, v110, v110
	v_fmac_f32_e32 v199, v112, v112
	v_pk_add_f32 v[98:99], v[98:99], v[200:201]
	v_add_f32_e32 v198, v198, v199
	v_mul_f32_e32 v199, v107, v107
	v_mul_f32_e32 v200, v109, v109
	v_fmac_f32_e32 v199, v106, v106
	v_fmac_f32_e32 v200, v108, v108
	v_pk_add_f32 v[102:103], v[102:103], v[202:203]
	v_add_f32_e32 v199, v199, v200
	v_add_f32_e32 v198, v198, v199
	v_mul_f32_e32 v199, v103, v103
	v_mul_f32_e32 v200, v105, v105
	v_fmac_f32_e32 v199, v102, v102
	v_fmac_f32_e32 v200, v104, v104
	v_add_f32_e32 v199, v199, v200
	v_add_f32_e32 v198, v198, v199
	v_mul_f32_e32 v199, v99, v99
	v_mul_f32_e32 v200, v101, v101
	v_fmac_f32_e32 v199, v98, v98
	v_fmac_f32_e32 v200, v100, v100
	v_add_f32_e32 v199, v199, v200
	v_add_f32_e32 v198, v198, v199
	ds_bpermute_b32 v199, v217, v198
	s_waitcnt lgkmcnt(0)
	v_add_f32_e32 v198, v198, v199
	ds_bpermute_b32 v199, v218, v198
	s_and_saveexec_b64 s[0:1], vcc
	s_cbranch_execz .LBB0_1025
	s_lshl_b32 s4, s35, 10
	s_add_i32 s4, s3, s4
	v_lshl_add_u32 v200, v212, 4, s4
	s_waitcnt lgkmcnt(0)
	v_add_f32_e32 v198, v198, v199
	ds_write_b32 v200, v198 offset:256
.LBB0_1025:
	s_or_b64 exec, exec, s[0:1]
	s_waitcnt vmcnt(23)
	v_lshlrev_b32_e32 v198, 16, v196
	s_waitcnt lgkmcnt(0)
	v_and_b32_e32 v199, 0xffff0000, v196
	v_lshlrev_b32_e32 v196, 16, v197
	v_and_b32_e32 v197, 0xffff0000, v197
	v_pk_add_f32 v[96:97], v[96:97], v[196:197]
	s_waitcnt vmcnt(22)
	v_lshlrev_b32_e32 v196, 16, v194
	v_and_b32_e32 v197, 0xffff0000, v194
	v_lshlrev_b32_e32 v194, 16, v195
	v_and_b32_e32 v195, 0xffff0000, v195
	v_pk_add_f32 v[92:93], v[92:93], v[194:195]
	s_waitcnt vmcnt(21)
	v_lshlrev_b32_e32 v194, 16, v192
	v_and_b32_e32 v195, 0xffff0000, v192
	v_lshlrev_b32_e32 v192, 16, v193
	v_and_b32_e32 v193, 0xffff0000, v193
	v_pk_add_f32 v[94:95], v[94:95], v[198:199]
	v_pk_add_f32 v[88:89], v[88:89], v[192:193]
	s_waitcnt vmcnt(20)
	v_lshlrev_b32_e32 v192, 16, v190
	v_and_b32_e32 v193, 0xffff0000, v190
	v_lshlrev_b32_e32 v190, 16, v191
	v_and_b32_e32 v191, 0xffff0000, v191
	v_pk_add_f32 v[84:85], v[84:85], v[190:191]
	v_mul_f32_e32 v190, v95, v95
	v_mul_f32_e32 v191, v97, v97
	v_pk_add_f32 v[90:91], v[90:91], v[196:197]
	v_fmac_f32_e32 v190, v94, v94
	v_fmac_f32_e32 v191, v96, v96
	v_pk_add_f32 v[82:83], v[82:83], v[192:193]
	v_add_f32_e32 v190, v190, v191
	v_mul_f32_e32 v191, v91, v91
	v_mul_f32_e32 v192, v93, v93
	v_fmac_f32_e32 v191, v90, v90
	v_fmac_f32_e32 v192, v92, v92
	v_pk_add_f32 v[86:87], v[86:87], v[194:195]
	v_add_f32_e32 v191, v191, v192
	v_add_f32_e32 v190, v190, v191
	v_mul_f32_e32 v191, v87, v87
	v_mul_f32_e32 v192, v89, v89
	v_fmac_f32_e32 v191, v86, v86
	v_fmac_f32_e32 v192, v88, v88
	v_add_f32_e32 v191, v191, v192
	v_add_f32_e32 v190, v190, v191
	v_mul_f32_e32 v191, v83, v83
	v_mul_f32_e32 v192, v85, v85
	v_fmac_f32_e32 v191, v82, v82
	v_fmac_f32_e32 v192, v84, v84
	v_add_f32_e32 v191, v191, v192
	v_add_f32_e32 v190, v190, v191
	ds_bpermute_b32 v191, v217, v190
	s_waitcnt lgkmcnt(0)
	v_add_f32_e32 v190, v190, v191
	ds_bpermute_b32 v191, v218, v190
	s_and_saveexec_b64 s[0:1], vcc
	s_cbranch_execz .LBB0_1027
	s_lshl_b32 s4, s35, 10
	s_add_i32 s4, s3, s4
	v_lshl_add_u32 v192, v212, 4, s4
	s_waitcnt lgkmcnt(0)
	v_add_f32_e32 v190, v190, v191
	ds_write_b32 v192, v190 offset:512
.LBB0_1027:
	s_or_b64 exec, exec, s[0:1]
	s_waitcnt vmcnt(19)
	v_lshlrev_b32_e32 v190, 16, v188
	s_waitcnt lgkmcnt(0)
	v_and_b32_e32 v191, 0xffff0000, v188
	v_lshlrev_b32_e32 v188, 16, v189
	v_and_b32_e32 v189, 0xffff0000, v189
	v_pk_add_f32 v[80:81], v[80:81], v[188:189]
	s_waitcnt vmcnt(18)
	v_lshlrev_b32_e32 v188, 16, v186
	v_and_b32_e32 v189, 0xffff0000, v186
	v_lshlrev_b32_e32 v186, 16, v187
	v_and_b32_e32 v187, 0xffff0000, v187
	v_pk_add_f32 v[76:77], v[76:77], v[186:187]
	s_waitcnt vmcnt(17)
	v_lshlrev_b32_e32 v186, 16, v184
	v_and_b32_e32 v187, 0xffff0000, v184
	v_lshlrev_b32_e32 v184, 16, v185
	v_and_b32_e32 v185, 0xffff0000, v185
	v_pk_add_f32 v[78:79], v[78:79], v[190:191]
	v_pk_add_f32 v[72:73], v[72:73], v[184:185]
	s_waitcnt vmcnt(16)
	v_lshlrev_b32_e32 v184, 16, v182
	v_and_b32_e32 v185, 0xffff0000, v182
	v_lshlrev_b32_e32 v182, 16, v183
	v_and_b32_e32 v183, 0xffff0000, v183
	v_pk_add_f32 v[68:69], v[68:69], v[182:183]
	v_mul_f32_e32 v182, v79, v79
	v_mul_f32_e32 v183, v81, v81
	v_pk_add_f32 v[74:75], v[74:75], v[188:189]
	v_fmac_f32_e32 v182, v78, v78
	v_fmac_f32_e32 v183, v80, v80
	v_pk_add_f32 v[66:67], v[66:67], v[184:185]
	v_add_f32_e32 v182, v182, v183
	v_mul_f32_e32 v183, v75, v75
	v_mul_f32_e32 v184, v77, v77
	v_fmac_f32_e32 v183, v74, v74
	v_fmac_f32_e32 v184, v76, v76
	v_pk_add_f32 v[70:71], v[70:71], v[186:187]
	v_add_f32_e32 v183, v183, v184
	v_add_f32_e32 v182, v182, v183
	v_mul_f32_e32 v183, v71, v71
	v_mul_f32_e32 v184, v73, v73
	v_fmac_f32_e32 v183, v70, v70
	v_fmac_f32_e32 v184, v72, v72
	v_add_f32_e32 v183, v183, v184
	v_add_f32_e32 v182, v182, v183
	v_mul_f32_e32 v183, v67, v67
	v_mul_f32_e32 v184, v69, v69
	v_fmac_f32_e32 v183, v66, v66
	v_fmac_f32_e32 v184, v68, v68
	v_add_f32_e32 v183, v183, v184
	v_add_f32_e32 v182, v182, v183
	ds_bpermute_b32 v183, v217, v182
	s_waitcnt lgkmcnt(0)
	v_add_f32_e32 v182, v182, v183
	ds_bpermute_b32 v183, v218, v182
	s_and_saveexec_b64 s[0:1], vcc
	s_cbranch_execz .LBB0_1029
	s_lshl_b32 s4, s35, 10
	s_add_i32 s4, s3, s4
	v_lshl_add_u32 v184, v212, 4, s4
	s_waitcnt lgkmcnt(0)
	v_add_f32_e32 v182, v182, v183
	ds_write_b32 v184, v182 offset:768
.LBB0_1029:
	s_or_b64 exec, exec, s[0:1]
	s_waitcnt vmcnt(15)
	v_lshlrev_b32_e32 v182, 16, v180
	s_waitcnt lgkmcnt(0)
	v_and_b32_e32 v183, 0xffff0000, v180
	v_lshlrev_b32_e32 v180, 16, v181
	v_and_b32_e32 v181, 0xffff0000, v181
	v_pk_add_f32 v[64:65], v[64:65], v[180:181]
	s_waitcnt vmcnt(14)
	v_lshlrev_b32_e32 v180, 16, v178
	v_and_b32_e32 v181, 0xffff0000, v178
	v_lshlrev_b32_e32 v178, 16, v179
	v_and_b32_e32 v179, 0xffff0000, v179
	v_pk_add_f32 v[60:61], v[60:61], v[178:179]
	s_waitcnt vmcnt(13)
	v_lshlrev_b32_e32 v178, 16, v176
	v_and_b32_e32 v179, 0xffff0000, v176
	v_lshlrev_b32_e32 v176, 16, v177
	v_and_b32_e32 v177, 0xffff0000, v177
	v_pk_add_f32 v[62:63], v[62:63], v[182:183]
	v_pk_add_f32 v[56:57], v[56:57], v[176:177]
	s_waitcnt vmcnt(12)
	v_lshlrev_b32_e32 v176, 16, v174
	v_and_b32_e32 v177, 0xffff0000, v174
	v_lshlrev_b32_e32 v174, 16, v175
	v_and_b32_e32 v175, 0xffff0000, v175
	v_pk_add_f32 v[52:53], v[52:53], v[174:175]
	v_mul_f32_e32 v174, v63, v63
	v_mul_f32_e32 v175, v65, v65
	v_pk_add_f32 v[58:59], v[58:59], v[180:181]
	v_fmac_f32_e32 v174, v62, v62
	v_fmac_f32_e32 v175, v64, v64
	v_pk_add_f32 v[50:51], v[50:51], v[176:177]
	v_add_f32_e32 v174, v174, v175
	v_mul_f32_e32 v175, v59, v59
	v_mul_f32_e32 v176, v61, v61
	v_fmac_f32_e32 v175, v58, v58
	v_fmac_f32_e32 v176, v60, v60
	v_pk_add_f32 v[54:55], v[54:55], v[178:179]
	v_add_f32_e32 v175, v175, v176
	v_add_f32_e32 v174, v174, v175
	v_mul_f32_e32 v175, v55, v55
	v_mul_f32_e32 v176, v57, v57
	v_fmac_f32_e32 v175, v54, v54
	v_fmac_f32_e32 v176, v56, v56
	v_add_f32_e32 v175, v175, v176
	v_add_f32_e32 v174, v174, v175
	v_mul_f32_e32 v175, v51, v51
	v_mul_f32_e32 v176, v53, v53
	v_fmac_f32_e32 v175, v50, v50
	v_fmac_f32_e32 v176, v52, v52
	v_add_f32_e32 v175, v175, v176
	v_add_f32_e32 v174, v174, v175
	ds_bpermute_b32 v175, v217, v174
	s_waitcnt lgkmcnt(0)
	v_add_f32_e32 v174, v174, v175
	ds_bpermute_b32 v175, v218, v174
	s_and_saveexec_b64 s[0:1], vcc
	s_cbranch_execz .LBB0_1031
	s_lshl_b32 s4, s35, 10
	s_add_i32 s4, s3, s4
	v_lshl_add_u32 v176, v212, 4, s4
	s_waitcnt lgkmcnt(0)
	v_add_f32_e32 v174, v174, v175
	ds_write_b32 v176, v174 offset:2048
.LBB0_1031:
	s_or_b64 exec, exec, s[0:1]
	s_waitcnt vmcnt(11)
	v_lshlrev_b32_e32 v174, 16, v172
	s_waitcnt lgkmcnt(0)
	v_and_b32_e32 v175, 0xffff0000, v172
	v_lshlrev_b32_e32 v172, 16, v173
	v_and_b32_e32 v173, 0xffff0000, v173
	v_pk_add_f32 v[48:49], v[48:49], v[172:173]
	s_waitcnt vmcnt(10)
	v_lshlrev_b32_e32 v172, 16, v170
	v_and_b32_e32 v173, 0xffff0000, v170
	v_lshlrev_b32_e32 v170, 16, v171
	v_and_b32_e32 v171, 0xffff0000, v171
	v_pk_add_f32 v[44:45], v[44:45], v[170:171]
	s_waitcnt vmcnt(9)
	v_lshlrev_b32_e32 v170, 16, v168
	v_and_b32_e32 v171, 0xffff0000, v168
	v_lshlrev_b32_e32 v168, 16, v169
	v_and_b32_e32 v169, 0xffff0000, v169
	v_pk_add_f32 v[46:47], v[46:47], v[174:175]
	v_pk_add_f32 v[40:41], v[40:41], v[168:169]
	s_waitcnt vmcnt(8)
	v_lshlrev_b32_e32 v168, 16, v166
	v_and_b32_e32 v169, 0xffff0000, v166
	v_lshlrev_b32_e32 v166, 16, v167
	v_and_b32_e32 v167, 0xffff0000, v167
	v_pk_add_f32 v[36:37], v[36:37], v[166:167]
	v_mul_f32_e32 v166, v47, v47
	v_mul_f32_e32 v167, v49, v49
	v_pk_add_f32 v[42:43], v[42:43], v[172:173]
	v_fmac_f32_e32 v166, v46, v46
	v_fmac_f32_e32 v167, v48, v48
	v_pk_add_f32 v[34:35], v[34:35], v[168:169]
	v_add_f32_e32 v166, v166, v167
	v_mul_f32_e32 v167, v43, v43
	v_mul_f32_e32 v168, v45, v45
	v_fmac_f32_e32 v167, v42, v42
	v_fmac_f32_e32 v168, v44, v44
	v_pk_add_f32 v[38:39], v[38:39], v[170:171]
	v_add_f32_e32 v167, v167, v168
	v_add_f32_e32 v166, v166, v167
	v_mul_f32_e32 v167, v39, v39
	v_mul_f32_e32 v168, v41, v41
	v_fmac_f32_e32 v167, v38, v38
	v_fmac_f32_e32 v168, v40, v40
	v_add_f32_e32 v167, v167, v168
	v_add_f32_e32 v166, v166, v167
	v_mul_f32_e32 v167, v35, v35
	v_mul_f32_e32 v168, v37, v37
	v_fmac_f32_e32 v167, v34, v34
	v_fmac_f32_e32 v168, v36, v36
	v_add_f32_e32 v167, v167, v168
	v_add_f32_e32 v166, v166, v167
	ds_bpermute_b32 v167, v217, v166
	s_waitcnt lgkmcnt(0)
	v_add_f32_e32 v166, v166, v167
	ds_bpermute_b32 v167, v218, v166
	s_and_saveexec_b64 s[0:1], vcc
	s_cbranch_execz .LBB0_1033
	s_lshl_b32 s4, s35, 10
	s_add_i32 s4, s3, s4
	v_lshl_add_u32 v168, v212, 4, s4
	s_waitcnt lgkmcnt(0)
	v_add_f32_e32 v166, v166, v167
	ds_write_b32 v168, v166 offset:2304
.LBB0_1033:
	s_or_b64 exec, exec, s[0:1]
	s_waitcnt vmcnt(7)
	v_lshlrev_b32_e32 v166, 16, v164
	s_waitcnt lgkmcnt(0)
	v_and_b32_e32 v167, 0xffff0000, v164
	v_lshlrev_b32_e32 v164, 16, v165
	v_and_b32_e32 v165, 0xffff0000, v165
	v_pk_add_f32 v[32:33], v[32:33], v[164:165]
	s_waitcnt vmcnt(6)
	v_lshlrev_b32_e32 v164, 16, v162
	v_and_b32_e32 v165, 0xffff0000, v162
	v_lshlrev_b32_e32 v162, 16, v163
	v_and_b32_e32 v163, 0xffff0000, v163
	v_pk_add_f32 v[28:29], v[28:29], v[162:163]
	s_waitcnt vmcnt(5)
	v_lshlrev_b32_e32 v162, 16, v160
	v_and_b32_e32 v163, 0xffff0000, v160
	v_lshlrev_b32_e32 v160, 16, v161
	v_and_b32_e32 v161, 0xffff0000, v161
	v_pk_add_f32 v[30:31], v[30:31], v[166:167]
	v_pk_add_f32 v[24:25], v[24:25], v[160:161]
	s_waitcnt vmcnt(4)
	v_lshlrev_b32_e32 v160, 16, v158
	v_and_b32_e32 v161, 0xffff0000, v158
	v_lshlrev_b32_e32 v158, 16, v159
	v_and_b32_e32 v159, 0xffff0000, v159
	v_pk_add_f32 v[20:21], v[20:21], v[158:159]
	v_mul_f32_e32 v158, v31, v31
	v_mul_f32_e32 v159, v33, v33
	v_pk_add_f32 v[26:27], v[26:27], v[164:165]
	v_fmac_f32_e32 v158, v30, v30
	v_fmac_f32_e32 v159, v32, v32
	v_pk_add_f32 v[18:19], v[18:19], v[160:161]
	v_add_f32_e32 v158, v158, v159
	v_mul_f32_e32 v159, v27, v27
	v_mul_f32_e32 v160, v29, v29
	v_fmac_f32_e32 v159, v26, v26
	v_fmac_f32_e32 v160, v28, v28
	v_pk_add_f32 v[22:23], v[22:23], v[162:163]
	v_add_f32_e32 v159, v159, v160
	v_add_f32_e32 v158, v158, v159
	v_mul_f32_e32 v159, v23, v23
	v_mul_f32_e32 v160, v25, v25
	v_fmac_f32_e32 v159, v22, v22
	v_fmac_f32_e32 v160, v24, v24
	v_add_f32_e32 v159, v159, v160
	v_add_f32_e32 v158, v158, v159
	v_mul_f32_e32 v159, v19, v19
	v_mul_f32_e32 v160, v21, v21
	v_fmac_f32_e32 v159, v18, v18
	v_fmac_f32_e32 v160, v20, v20
	v_add_f32_e32 v159, v159, v160
	v_add_f32_e32 v158, v158, v159
	ds_bpermute_b32 v159, v217, v158
	s_waitcnt lgkmcnt(0)
	v_add_f32_e32 v158, v158, v159
	ds_bpermute_b32 v159, v218, v158
	s_and_saveexec_b64 s[0:1], vcc
	s_cbranch_execz .LBB0_1035
	s_lshl_b32 s4, s35, 10
	s_add_i32 s4, s3, s4
	v_lshl_add_u32 v160, v212, 4, s4
	s_waitcnt lgkmcnt(0)
	v_add_f32_e32 v158, v158, v159
	ds_write_b32 v160, v158 offset:2560
.LBB0_1035:
	s_or_b64 exec, exec, s[0:1]
	s_waitcnt vmcnt(3)
	v_lshlrev_b32_e32 v158, 16, v156
	s_waitcnt lgkmcnt(0)
	v_and_b32_e32 v159, 0xffff0000, v156
	v_pk_add_f32 v[164:165], v[14:15], v[158:159]
	s_waitcnt vmcnt(2)
	v_lshlrev_b32_e32 v14, 16, v154
	v_and_b32_e32 v15, 0xffff0000, v154
	v_lshlrev_b32_e32 v156, 16, v157
	v_and_b32_e32 v157, 0xffff0000, v157
	v_pk_add_f32 v[162:163], v[10:11], v[14:15]
	s_waitcnt vmcnt(1)
	v_lshlrev_b32_e32 v10, 16, v152
	v_and_b32_e32 v11, 0xffff0000, v152
	v_pk_add_f32 v[160:161], v[16:17], v[156:157]
	v_lshlrev_b32_e32 v16, 16, v155
	v_and_b32_e32 v17, 0xffff0000, v155
	v_pk_add_f32 v[158:159], v[6:7], v[10:11]
	s_waitcnt vmcnt(0)
	v_lshlrev_b32_e32 v6, 16, v150
	v_and_b32_e32 v7, 0xffff0000, v150
	v_pk_add_f32 v[154:155], v[12:13], v[16:17]
	v_lshlrev_b32_e32 v12, 16, v153
	v_and_b32_e32 v13, 0xffff0000, v153
	v_pk_add_f32 v[156:157], v[2:3], v[6:7]
	v_mul_f32_e32 v2, v165, v165
	v_mul_f32_e32 v3, v161, v161
	v_pk_add_f32 v[152:153], v[8:9], v[12:13]
	v_lshlrev_b32_e32 v8, 16, v151
	v_and_b32_e32 v9, 0xffff0000, v151
	v_fmac_f32_e32 v2, v164, v164
	v_fmac_f32_e32 v3, v160, v160
	v_pk_add_f32 v[150:151], v[4:5], v[8:9]
	v_add_f32_e32 v2, v2, v3
	v_mul_f32_e32 v3, v163, v163
	v_mul_f32_e32 v4, v155, v155
	v_fmac_f32_e32 v3, v162, v162
	v_fmac_f32_e32 v4, v154, v154
	v_add_f32_e32 v3, v3, v4
	v_add_f32_e32 v2, v2, v3
	v_mul_f32_e32 v3, v159, v159
	v_mul_f32_e32 v4, v153, v153
	v_fmac_f32_e32 v3, v158, v158
	v_fmac_f32_e32 v4, v152, v152
	v_add_f32_e32 v3, v3, v4
	v_add_f32_e32 v2, v2, v3
	v_mul_f32_e32 v3, v157, v157
	v_mul_f32_e32 v4, v151, v151
	v_fmac_f32_e32 v3, v156, v156
	v_fmac_f32_e32 v4, v150, v150
	v_add_f32_e32 v3, v3, v4
	v_add_f32_e32 v2, v2, v3
	ds_bpermute_b32 v3, v217, v2
	s_waitcnt lgkmcnt(0)
	v_add_f32_e32 v2, v2, v3
	ds_bpermute_b32 v3, v218, v2
	s_and_saveexec_b64 s[0:1], vcc
	s_cbranch_execz .LBB0_1037
	s_lshl_b32 s4, s35, 10
	s_add_i32 s3, s3, s4
	v_lshl_add_u32 v4, v212, 4, s3
	s_waitcnt lgkmcnt(0)
	v_add_f32_e32 v2, v2, v3
	ds_write_b32 v4, v2 offset:2816
